# grid barrier: the acquire-side cache invalidate kept only at the two seams (after out-proj, after up-proj) where a stale or partially written line can exist; removed at the other six
# speedup vs baseline: 1.0128x; 1.0128x over previous
; __device__ __forceinline__ unsigned xb_ld(unsigned* p)              { return __hip_atomic_load(p, __ATOMIC_RELAXED, __HIP_MEMORY_SCOPE_AGENT); }
; #define XB_SPIN(cond, bar) do { unsigned _sp = 0; while (cond) { __builtin_amdgcn_s_sleep(1); \
;     if ((++_sp & 255u) == 0u) { if (xb_ld(&(bar)[XB_TMO])) break; if (_sp > XB_SPIN_CAP) { atomicAdd(&(bar)[XB_TMO], 1u); break; } } } } while (0)
; __device__ __forceinline__ void xcd_barrier(const XcdBarrier& b) {
;     ...
;         } else {
;             XB_SPIN(xb_ld(&bar[XB_XGEN(b.x)]) == gen, bar);
;             __builtin_amdgcn_fence(__ATOMIC_ACQUIRE, "agent");
;             asm volatile("s_waitcnt vmcnt(0)" ::: "memory");
;         }
.LBB0_66:
	s_or_b64 exec, exec, s[10:11]
	s_waitcnt vmcnt(0)
	s_waitcnt vmcnt(0)

; __device__ __forceinline__ unsigned xb_ld(unsigned* p)              { return __hip_atomic_load(p, __ATOMIC_RELAXED, __HIP_MEMORY_SCOPE_AGENT); }
; __device__ __forceinline__ unsigned xb_add(unsigned* p, unsigned v) { return __hip_atomic_fetch_add(p, v, __ATOMIC_RELAXED, __HIP_MEMORY_SCOPE_AGENT); }
; #define XB_SPIN(cond, bar) do { unsigned _sp = 0; while (cond) { __builtin_amdgcn_s_sleep(1); \
;     if ((++_sp & 255u) == 0u) { if (xb_ld(&(bar)[XB_TMO])) break; if (_sp > XB_SPIN_CAP) { atomicAdd(&(bar)[XB_TMO], 1u); break; } } } } while (0)
; __device__ __forceinline__ void xcd_barrier(const XcdBarrier& b) {
;     ...
;         if (old + 1u == (gen + 1u) * nloc) {
;             __builtin_amdgcn_fence(__ATOMIC_RELEASE, "agent");
;             asm volatile("s_waitcnt vmcnt(0)" ::: "memory");
;             const unsigned og = xb_add(&bar[XB_TOP], 1u);
;             const unsigned tg = og / nx;
;             if (og + 1u == (tg + 1u) * nx) xb_add(&bar[XB_TOPGEN], 1u);
;             else XB_SPIN(xb_ld(&bar[XB_TOPGEN]) == tg, bar);
;             __builtin_amdgcn_fence(__ATOMIC_ACQUIRE, "agent");
;             xb_add(&bar[XB_XGEN(b.x)], 1u);
;             asm volatile("s_waitcnt vmcnt(0)" ::: "memory");
.LBB0_84:
	s_or_b64 exec, exec, s[4:5]
	s_mov_b64 s[4:5], exec
	v_mbcnt_lo_u32_b32 v0, s4, 0
	v_mbcnt_hi_u32_b32 v0, s5, v0
	v_cmp_eq_u32_e32 vcc, 0, v0
	s_waitcnt vmcnt(0)
	s_and_saveexec_b64 s[10:11], vcc
	s_cbranch_execz .LBB0_86
	s_bcnt1_i32_b64 s4, s[4:5]
	v_mov_b32_e32 v0, 0x2000
	v_mov_b32_e32 v1, s4
	global_atomic_add v0, v1, s[2:3] offset:1024

; __device__ __forceinline__ unsigned xb_ld(unsigned* p)              { return __hip_atomic_load(p, __ATOMIC_RELAXED, __HIP_MEMORY_SCOPE_AGENT); }
; #define XB_SPIN(cond, bar) do { unsigned _sp = 0; while (cond) { __builtin_amdgcn_s_sleep(1); \
;     if ((++_sp & 255u) == 0u) { if (xb_ld(&(bar)[XB_TMO])) break; if (_sp > XB_SPIN_CAP) { atomicAdd(&(bar)[XB_TMO], 1u); break; } } } } while (0)
; __device__ __forceinline__ void xcd_barrier(const XcdBarrier& b) {
;     ...
;         } else {
;             XB_SPIN(xb_ld(&bar[XB_XGEN(b.x)]) == gen, bar);
;             __builtin_amdgcn_fence(__ATOMIC_ACQUIRE, "agent");
;             asm volatile("s_waitcnt vmcnt(0)" ::: "memory");
;         }
.LBB0_204:
	s_or_b64 exec, exec, s[8:9]
	s_waitcnt vmcnt(0)
	s_waitcnt vmcnt(0)

; __device__ __forceinline__ unsigned xb_ld(unsigned* p)              { return __hip_atomic_load(p, __ATOMIC_RELAXED, __HIP_MEMORY_SCOPE_AGENT); }
; __device__ __forceinline__ unsigned xb_add(unsigned* p, unsigned v) { return __hip_atomic_fetch_add(p, v, __ATOMIC_RELAXED, __HIP_MEMORY_SCOPE_AGENT); }
; #define XB_SPIN(cond, bar) do { unsigned _sp = 0; while (cond) { __builtin_amdgcn_s_sleep(1); \
;     if ((++_sp & 255u) == 0u) { if (xb_ld(&(bar)[XB_TMO])) break; if (_sp > XB_SPIN_CAP) { atomicAdd(&(bar)[XB_TMO], 1u); break; } } } } while (0)
; __device__ __forceinline__ void xcd_barrier(const XcdBarrier& b) {
;     ...
;         if (old + 1u == (gen + 1u) * nloc) {
;             __builtin_amdgcn_fence(__ATOMIC_RELEASE, "agent");
;             asm volatile("s_waitcnt vmcnt(0)" ::: "memory");
;             const unsigned og = xb_add(&bar[XB_TOP], 1u);
;             const unsigned tg = og / nx;
;             if (og + 1u == (tg + 1u) * nx) xb_add(&bar[XB_TOPGEN], 1u);
;             else XB_SPIN(xb_ld(&bar[XB_TOPGEN]) == tg, bar);
;             __builtin_amdgcn_fence(__ATOMIC_ACQUIRE, "agent");
;             xb_add(&bar[XB_XGEN(b.x)], 1u);
;             asm volatile("s_waitcnt vmcnt(0)" ::: "memory");
.LBB0_222:
	s_or_b64 exec, exec, s[4:5]
	s_mov_b64 s[4:5], exec
	v_mbcnt_lo_u32_b32 v0, s4, 0
	v_mbcnt_hi_u32_b32 v0, s5, v0
	v_cmp_eq_u32_e32 vcc, 0, v0
	s_waitcnt vmcnt(0)
	s_and_saveexec_b64 s[8:9], vcc
	s_cbranch_execz .LBB0_224
	s_bcnt1_i32_b64 s4, s[4:5]
	v_mov_b32_e32 v0, 0x2000
	v_mov_b32_e32 v1, s4
	global_atomic_add v0, v1, s[2:3] offset:1024

; __device__ __forceinline__ unsigned xb_ld(unsigned* p)              { return __hip_atomic_load(p, __ATOMIC_RELAXED, __HIP_MEMORY_SCOPE_AGENT); }
; __device__ __forceinline__ unsigned xb_add(unsigned* p, unsigned v) { return __hip_atomic_fetch_add(p, v, __ATOMIC_RELAXED, __HIP_MEMORY_SCOPE_AGENT); }
; #define XB_SPIN(cond, bar) do { unsigned _sp = 0; while (cond) { __builtin_amdgcn_s_sleep(1); \
;     if ((++_sp & 255u) == 0u) { if (xb_ld(&(bar)[XB_TMO])) break; if (_sp > XB_SPIN_CAP) { atomicAdd(&(bar)[XB_TMO], 1u); break; } } } } while (0)
; __device__ __forceinline__ void xcd_barrier(const XcdBarrier& b) {
;     ...
;         if (old + 1u == (gen + 1u) * nloc) {
;             __builtin_amdgcn_fence(__ATOMIC_RELEASE, "agent");
;             asm volatile("s_waitcnt vmcnt(0)" ::: "memory");
;             const unsigned og = xb_add(&bar[XB_TOP], 1u);
;             const unsigned tg = og / nx;
;             if (og + 1u == (tg + 1u) * nx) xb_add(&bar[XB_TOPGEN], 1u);
;             else XB_SPIN(xb_ld(&bar[XB_TOPGEN]) == tg, bar);
;             __builtin_amdgcn_fence(__ATOMIC_ACQUIRE, "agent");
;             xb_add(&bar[XB_XGEN(b.x)], 1u);
;             asm volatile("s_waitcnt vmcnt(0)" ::: "memory");
.LBB0_399:
	s_or_b64 exec, exec, s[6:7]
	s_mov_b64 s[6:7], exec
	v_mbcnt_lo_u32_b32 v0, s6, 0
	v_mbcnt_hi_u32_b32 v0, s7, v0
	v_cmp_eq_u32_e32 vcc, 0, v0
	s_waitcnt vmcnt(0)
	s_and_saveexec_b64 s[8:9], vcc
	s_cbranch_execz .LBB0_401
	s_bcnt1_i32_b64 s6, s[6:7]
	v_mov_b32_e32 v0, 0x2000
	v_mov_b32_e32 v1, s6
	global_atomic_add v0, v1, s[2:3] offset:1024

; __device__ __forceinline__ unsigned xb_ld(unsigned* p)              { return __hip_atomic_load(p, __ATOMIC_RELAXED, __HIP_MEMORY_SCOPE_AGENT); }
; __device__ __forceinline__ unsigned xb_add(unsigned* p, unsigned v) { return __hip_atomic_fetch_add(p, v, __ATOMIC_RELAXED, __HIP_MEMORY_SCOPE_AGENT); }
; #define XB_SPIN(cond, bar) do { unsigned _sp = 0; while (cond) { __builtin_amdgcn_s_sleep(1); \
;     if ((++_sp & 255u) == 0u) { if (xb_ld(&(bar)[XB_TMO])) break; if (_sp > XB_SPIN_CAP) { atomicAdd(&(bar)[XB_TMO], 1u); break; } } } } while (0)
; __device__ __forceinline__ void xcd_barrier(const XcdBarrier& b) {
;     ...
;         if (old + 1u == (gen + 1u) * nloc) {
;             __builtin_amdgcn_fence(__ATOMIC_RELEASE, "agent");
;             asm volatile("s_waitcnt vmcnt(0)" ::: "memory");
;             const unsigned og = xb_add(&bar[XB_TOP], 1u);
;             const unsigned tg = og / nx;
;             if (og + 1u == (tg + 1u) * nx) xb_add(&bar[XB_TOPGEN], 1u);
;             else XB_SPIN(xb_ld(&bar[XB_TOPGEN]) == tg, bar);
;             __builtin_amdgcn_fence(__ATOMIC_ACQUIRE, "agent");
;             xb_add(&bar[XB_XGEN(b.x)], 1u);
;             asm volatile("s_waitcnt vmcnt(0)" ::: "memory");
.LBB0_777:
	s_or_b64 exec, exec, s[8:9]
	s_mov_b64 s[8:9], exec
	v_mbcnt_lo_u32_b32 v0, s8, 0
	v_mbcnt_hi_u32_b32 v0, s9, v0
	v_cmp_eq_u32_e32 vcc, 0, v0
	s_waitcnt vmcnt(0)
	s_and_saveexec_b64 s[10:11], vcc
	s_cbranch_execz .LBB0_779
	s_bcnt1_i32_b64 s8, s[8:9]
	v_mov_b32_e32 v0, 0x2000
	v_mov_b32_e32 v1, s8
	global_atomic_add v0, v1, s[2:3] offset:1024
